# P1: sample rows normalised by waves 0-1 of every workgroup in a hand-written tail instead of a 17th row on workgroups 0..63
# baseline (speedup 1.0000x reference)
; __device__ __forceinline__ unsigned cvt_pk_bf16(float lo, float hi) { unsigned r; asm("v_cvt_pk_bf16_f32 %0, %1, %2" : "=v"(r) : "v"(lo), "v"(hi)); return r; }
; __device__ __forceinline__ void norm_load(const float* xrow, f32x4 (&v)[4], int lane) {
; #pragma unroll
;     for (int j = 0; j < 4; ++j) v[j] = __builtin_nontemporal_load((const f32x4*)xrow + lane + 64 * j);
; }
; __device__ __forceinline__ void norm_apply(const f32x4 (&v)[4], const float* g, const float* sc, const float* sh, bf16_t* orow, int lane) {
;     float s = 0.f;
; #pragma unroll
;     for (int j = 0; j < 4; ++j) s += (v[j][0] * v[j][0] + v[j][1] * v[j][1]) + (v[j][2] * v[j][2] + v[j][3] * v[j][3]);
;     const float rstd = rsqrtf(wave_sum(s) * (1.f / 1024.f) + EPS);
; #pragma unroll
;     for (int j = 0; j < 4; ++j) { const int c4 = lane + 64 * j;
;         const f32x4 gg = *((const f32x4*)g + c4), cc = *((const f32x4*)sc + c4), hh = *((const f32x4*)sh + c4);
;         const f32x4 h = v[j] * rstd * gg * (cc + 1.f) + hh;
;         u32x2 w; w.x = cvt_pk_bf16(h[0], h[1]); w.y = cvt_pk_bf16(h[2], h[3]);
;         *((u32x2*)orow + c4) = w; }
; }
; __global__ void __launch_bounds__(512, 2) mega_fwd(Args a) {
;     ...
;         int row = bx * 8 + wid; f32x4 nv[4];
;         if (row < MT) norm_load(row < MP ? x_p + (size_t)row * DM : x_s + (size_t)(row - MP) * DM, nv, lane);
;         for (; row < MT; row += G * 8) {
;             f32x4 v[4];
; #pragma unroll
;             for (int j = 0; j < 4; ++j) v[j] = nv[j];
;             const int nr = row + G * 8;
;             if (nr < MT) norm_load(nr < MP ? x_p + (size_t)nr * DM : x_s + (size_t)(nr - MP) * DM, nv, lane);
;             const int b16 = row < MP ? (row >> 12) : 8 + ((row - MP) >> 6);
;             norm_apply(v, norm1_g, MOD + (size_t)b16 * 6144 + 1024, MOD + (size_t)b16 * 6144, Hb + (size_t)row * DM, lane);
.LBB0_241:
	s_add_i32 s18, s10, s12
	s_cmp_gt_i32 s18, 0x7fff
	s_cselect_b64 s[4:5], -1, 0
	s_and_b64 vcc, exec, s[4:5]
	v_lshlrev_b32_e32 v47, 4, v32
	s_cbranch_vccnz .LBB0_240
	s_add_i32 s11, s6, 0xffff8000
	s_cmp_lt_i32 s18, 0x8000
	v_readlane_b32 s36, v238, 4
	s_cselect_b32 s17, s7, 0
	s_cselect_b32 s16, s6, s11
	v_readlane_b32 s37, v238, 5
	v_readlane_b32 s38, v238, 6
	v_readlane_b32 s39, v238, 7
	s_cselect_b32 s11, s37, s39
	s_cselect_b32 s19, s36, s38
	s_lshl_b64 s[16:17], s[16:17], 12
	s_add_u32 s16, s19, s16
	s_addc_u32 s17, s11, s17
	global_load_dwordx4 v[16:19], v47, s[16:17] nt
	global_load_dwordx4 v[20:23], v47, s[16:17] offset:1024 nt
	global_load_dwordx4 v[24:27], v47, s[16:17] offset:2048 nt
	global_load_dwordx4 v[28:31], v47, s[16:17] offset:3072 nt
	v_readlane_b32 s40, v238, 8
	v_readlane_b32 s41, v238, 9
	v_readlane_b32 s42, v238, 10
	v_readlane_b32 s43, v238, 11
	v_readlane_b32 s44, v238, 12
	v_readlane_b32 s45, v238, 13
	v_readlane_b32 s46, v238, 14
	v_readlane_b32 s47, v238, 15
	v_readlane_b32 s48, v238, 16
	v_readlane_b32 s49, v238, 17
	v_readlane_b32 s50, v238, 18
	v_readlane_b32 s51, v238, 19
	s_branch .LBB0_240
.LBB0_243:
	v_readfirstlane_b32 s0, v211
	s_ashr_i32 s0, s0, 6
	s_cmp_gt_u32 s0, 1
	s_cbranch_scc1 .Lp1t_done
	v_readlane_b32 s1, v238, 46
	s_lshr_b32 s1, s1, 3
	s_lshl_b32 s0, s0, 8
	s_add_i32 s10, s0, s1
	v_and_b32_e32 v4, 63, v211
	v_lshlrev_b32_e32 v0, 4, v4
	v_lshlrev_b32_e32 v1, 3, v4
	v_xor_b32_e32 v2, 1, v4
	v_lshlrev_b32_e32 v2, 2, v2
	v_xor_b32_e32 v3, 2, v4
	v_lshlrev_b32_e32 v3, 2, v3
	v_xor_b32_e32 v5, 4, v4
	v_lshlrev_b32_e32 v5, 2, v5
	v_xor_b32_e32 v6, 8, v4
	v_lshlrev_b32_e32 v6, 2, v6
	v_xor_b32_e32 v7, 16, v4
	v_lshlrev_b32_e32 v7, 2, v7
	v_xor_b32_e32 v8, 32, v4
	v_lshlrev_b32_e32 v8, 2, v8
	v_readlane_b32 s4, v238, 6
	v_readlane_b32 s5, v238, 7
	s_lshl_b32 s3, s10, 12
	s_add_u32 s4, s4, s3
	s_addc_u32 s5, s5, 0
	global_load_dwordx4 v[96:99], v0, s[4:5] nt
	global_load_dwordx4 v[100:103], v0, s[4:5] offset:1024 nt
	global_load_dwordx4 v[104:107], v0, s[4:5] offset:2048 nt
	global_load_dwordx4 v[108:111], v0, s[4:5] offset:3072 nt
	global_load_dwordx4 v[16:19], v0, s[52:53]
	global_load_dwordx4 v[20:23], v0, s[52:53] offset:1024
	global_load_dwordx4 v[24:27], v0, s[52:53] offset:2048
	global_load_dwordx4 v[28:31], v0, s[52:53] offset:3072
	s_lshr_b32 s3, s10, 6
	s_add_i32 s3, s3, 8
	s_mul_i32 s3, s3, 0x6000
	s_add_u32 s6, s30, s3
	s_addc_u32 s7, s31, 0
	s_add_u32 s4, s6, 0x1000
	s_addc_u32 s5, s7, 0
	global_load_dwordx4 v[32:35], v0, s[4:5]
	global_load_dwordx4 v[36:39], v0, s[4:5] offset:1024
	global_load_dwordx4 v[40:43], v0, s[4:5] offset:2048
	global_load_dwordx4 v[44:47], v0, s[4:5] offset:3072
	global_load_dwordx4 v[48:51], v0, s[6:7]
	global_load_dwordx4 v[52:55], v0, s[6:7] offset:1024
	global_load_dwordx4 v[56:59], v0, s[6:7] offset:2048
	global_load_dwordx4 v[60:63], v0, s[6:7] offset:3072
	s_add_i32 s3, s10, 0x8000
	s_lshl_b32 s16, s3, 11
	s_add_u32 s16, s30, s16
	s_addc_u32 s17, s31, 0
	s_add_u32 s16, s16, 0x1d00000
	s_addc_u32 s17, s17, 0
	s_waitcnt vmcnt(12)
	v_mul_f32_e32 v9, v96, v96
	v_mul_f32_e32 v10, v97, v97
	v_fmac_f32_e32 v9, v98, v98
	v_fmac_f32_e32 v10, v99, v99
	v_fmac_f32_e32 v9, v100, v100
	v_fmac_f32_e32 v10, v101, v101
	v_fmac_f32_e32 v9, v102, v102
	v_fmac_f32_e32 v10, v103, v103
	v_fmac_f32_e32 v9, v104, v104
	v_fmac_f32_e32 v10, v105, v105
	v_fmac_f32_e32 v9, v106, v106
	v_fmac_f32_e32 v10, v107, v107
	v_fmac_f32_e32 v9, v108, v108
	v_fmac_f32_e32 v10, v109, v109
	v_fmac_f32_e32 v9, v110, v110
	v_fmac_f32_e32 v10, v111, v111
	v_add_f32_e32 v9, v9, v10
	ds_bpermute_b32 v10, v2, v9
	s_waitcnt lgkmcnt(0)
	v_add_f32_e32 v9, v9, v10
	ds_bpermute_b32 v10, v3, v9
	s_waitcnt lgkmcnt(0)
	v_add_f32_e32 v9, v9, v10
	ds_bpermute_b32 v10, v5, v9
	s_waitcnt lgkmcnt(0)
	v_add_f32_e32 v9, v9, v10
	ds_bpermute_b32 v10, v6, v9
	s_waitcnt lgkmcnt(0)
	v_add_f32_e32 v9, v9, v10
	ds_bpermute_b32 v10, v7, v9
	s_waitcnt lgkmcnt(0)
	v_add_f32_e32 v9, v9, v10
	ds_bpermute_b32 v10, v8, v9
	s_waitcnt lgkmcnt(0)
	v_add_f32_e32 v9, v9, v10
	v_mov_b32_e32 v10, 0x358637bd
	v_fmac_f32_e32 v10, 0x3a800000, v9
	v_rsq_f32_e32 v11, v10
	s_waitcnt vmcnt(0)
	v_mul_f32_e32 v96, v11, v96
	v_mul_f32_e32 v97, v11, v97
	v_mul_f32_e32 v98, v11, v98
	v_mul_f32_e32 v99, v11, v99
	v_mul_f32_e32 v100, v11, v100
	v_mul_f32_e32 v101, v11, v101
	v_mul_f32_e32 v102, v11, v102
	v_mul_f32_e32 v103, v11, v103
	v_mul_f32_e32 v104, v11, v104
	v_mul_f32_e32 v105, v11, v105
	v_mul_f32_e32 v106, v11, v106
	v_mul_f32_e32 v107, v11, v107
	v_mul_f32_e32 v108, v11, v108
	v_mul_f32_e32 v109, v11, v109
	v_mul_f32_e32 v110, v11, v110
	v_mul_f32_e32 v111, v11, v111
	v_mul_f32_e32 v96, v16, v96
	v_mul_f32_e32 v97, v17, v97
	v_mul_f32_e32 v98, v18, v98
	v_mul_f32_e32 v99, v19, v99
	v_mul_f32_e32 v100, v20, v100
	v_mul_f32_e32 v101, v21, v101
	v_mul_f32_e32 v102, v22, v102
	v_mul_f32_e32 v103, v23, v103
	v_mul_f32_e32 v104, v24, v104
	v_mul_f32_e32 v105, v25, v105
	v_mul_f32_e32 v106, v26, v106
	v_mul_f32_e32 v107, v27, v107
	v_mul_f32_e32 v108, v28, v108
	v_mul_f32_e32 v109, v29, v109
	v_mul_f32_e32 v110, v30, v110
	v_mul_f32_e32 v111, v31, v111
	v_add_f32_e32 v32, 1.0, v32
	v_add_f32_e32 v33, 1.0, v33
	v_add_f32_e32 v34, 1.0, v34
	v_add_f32_e32 v35, 1.0, v35
	v_add_f32_e32 v36, 1.0, v36
	v_add_f32_e32 v37, 1.0, v37
	v_add_f32_e32 v38, 1.0, v38
	v_add_f32_e32 v39, 1.0, v39
	v_add_f32_e32 v40, 1.0, v40
	v_add_f32_e32 v41, 1.0, v41
	v_add_f32_e32 v42, 1.0, v42
	v_add_f32_e32 v43, 1.0, v43
	v_add_f32_e32 v44, 1.0, v44
	v_add_f32_e32 v45, 1.0, v45
	v_add_f32_e32 v46, 1.0, v46
	v_add_f32_e32 v47, 1.0, v47
	v_fma_f32 v96, v32, v96, v48
	v_fma_f32 v97, v33, v97, v49
	v_fma_f32 v98, v34, v98, v50
	v_fma_f32 v99, v35, v99, v51
	v_fma_f32 v100, v36, v100, v52
	v_fma_f32 v101, v37, v101, v53
	v_fma_f32 v102, v38, v102, v54
	v_fma_f32 v103, v39, v103, v55
	v_fma_f32 v104, v40, v104, v56
	v_fma_f32 v105, v41, v105, v57
	v_fma_f32 v106, v42, v106, v58
	v_fma_f32 v107, v43, v107, v59
	v_fma_f32 v108, v44, v108, v60
	v_fma_f32 v109, v45, v109, v61
	v_fma_f32 v110, v46, v110, v62
	v_fma_f32 v111, v47, v111, v63
	v_cvt_pk_bf16_f32 v96, v96, v97
	v_cvt_pk_bf16_f32 v97, v98, v99
	v_cvt_pk_bf16_f32 v98, v100, v101
	v_cvt_pk_bf16_f32 v99, v102, v103
	v_cvt_pk_bf16_f32 v100, v104, v105
	v_cvt_pk_bf16_f32 v101, v106, v107
	v_cvt_pk_bf16_f32 v102, v108, v109
	v_cvt_pk_bf16_f32 v103, v110, v111
	global_store_dwordx2 v1, v[96:97], s[16:17]
	global_store_dwordx2 v1, v[98:99], s[16:17] offset:512
	global_store_dwordx2 v1, v[100:101], s[16:17] offset:1024
	global_store_dwordx2 v1, v[102:103], s[16:17] offset:1536
